# dense attention item prologue: tile-1 K/V staging loads issued with tile 0 and the Q rows (one exposed round trip less per item), copies at the old load site
# baseline (speedup 1.0000x reference)
; DI int fresh_lane() { int l; asm volatile("v_mbcnt_lo_u32_b32 %0, -1, 0\n\tv_mbcnt_hi_u32_b32 %0, -1, %0" : "=v"(l)); return l; }
; __device__ __forceinline__ int v_st(int k, int c) { const int kk = (k & ~0xC) | ((k & 4) << 1) | ((k & 8) >> 1); return ((kk >> 3) * 4 + (c >> 5)) * 512 + ((kk & 7) * 32 + (c & 31)) * 2; }
; template <typename TQ>
; __device__ __forceinline__ void attn_dense_body(const TQ* __restrict__ Qb, const bf16* __restrict__ Kh, const bf16* __restrict__ Vh,
;                                                 bf16* __restrict__ Ob, int seq, char* lds, const int tid) {
;     ...
;   const int wid = __builtin_amdgcn_readfirstlane(tid >> 6), lane = tid & 63, r32 = lane & 31, hi = lane >> 5;
;   bf16* V_lds = (bf16*)lds; bf16* K_lds = (bf16*)(lds + 2 * SHM_V);
;   float* ws = (float*)(lds + 2 * SHM_V + 2 * SHM_K) + wid * 64; float* li_l = ws; float* al_l = ws + 32;
;   float m_reg = -1e30f, l_reg = 0; f32x16 o[4] = {}; bf16x8 qr[8];
;   const TQ* Qw = Qb + (long)(wid * QBLK + r32) * LDQ + hi * 8;
; #pragma unroll
;   for (int d0 = 0; d0 < 8; ++d0) qr[d0] = SQ::tobf(SQ::ld8(Qw + d0 * 16));
;   const int sr = tid >> 4, sc = (tid & 15) * 8, vst0 = v_st(sr, sc), vst1 = v_st(32 + sr, sc);
;   const int vb0 = (int)(uintptr_t)V_lds + v_rd_base(lane);
;   struct { typename St::T vs0, vs1, ks0, ks1; } sr_[SDEPTH];
;     ...
;   f32x16 pA0, pA1, pB0, pB1; float mnA, mnB, alA, alB; bf16x8 pa0, pa1, pa2, pa3; const int NT = seq / KVBLK;
;   constexpr int SE = 0, SO = SDEPTH - 1;
;   SLOAD(SE, 0); asm volatile("s_waitcnt vmcnt(0)" ::: "memory"); SWRITE(0, SE); __syncthreads();
;   qkt(pA0, pA1, K_lds, qr, r32, hi); partialSM(pA0, pA1, m_reg, mnA, alA);
;   SLOAD(SO, KVBLK); if constexpr (SDEPTH == 2) { if (2 < NT) SLOAD(SE, 2 * KVBLK); }
; __global__ void __launch_bounds__(512, 2) fwd_kernel(Params p) {
;     ...
;             const int qb = item & 15, head = (item >> 4) & 7, b = item >> 7, kvh = head >> 2;
;             int tl = wave * 64 + fresh_lane(); asm volatile("" : "+v"(tl));
;             const size_t qrow = (size_t)NCTX + (size_t)b * SEQ + qb * 256;
;             __syncthreads();
;             adb::attn_dense_body<adb::bf16>(BIG1 + qrow * NIN1 + head * 128, VT + (size_t)(b * 2 + kvh) * KVLEN * 128, (const bf16*)(ws + WS_V1) + (size_t)(b * 2 + kvh) * KVLEN * 128,
.LBB0_1528:
	s_lshr_b32 s5, s2, 4
	s_ashr_i32 s4, s2, 7
	s_bfe_u32 s16, s5, 0x10002
	s_ashr_i32 s5, s4, 31
	s_lshl_b64 s[6:7], s[4:5], 12
	s_lshl_b32 s5, s2, 8
	s_and_b32 s5, s5, 0xf00
	s_bfe_u32 s8, s2, 0x30004
	s_or_b32 s5, s6, s5
	s_add_u32 s18, s5, 0x800
	s_addc_u32 s19, s7, 0
	s_mul_i32 s5, s19, 0xc00
	s_mul_hi_u32 s6, s18, 0xc00
	s_add_i32 s6, s6, s5
	s_mul_i32 s5, s18, 0xc00
	s_add_u32 s5, s24, s5
	s_addc_u32 s6, s25, s6
	s_lshl_b32 s15, s8, 7
	s_lshl_b32 s7, s8, 8
	s_add_u32 s8, s5, s7
	s_addc_u32 s9, s6, 0
	s_lshl_b32 s4, s4, 1
	v_mbcnt_lo_u32_b32 v0, -1, 0
	v_mbcnt_hi_u32_b32 v0, -1, v0
	s_or_b32 s16, s16, s4
	v_add_u32_e32 v52, s74, v0
	s_mul_i32 s6, s16, 0x110000
	v_readlane_b32 s4, v254, 14
	v_ashrrev_i32_e32 v16, 4, v52
	s_mul_hi_i32 s7, s16, 0x110000
	v_readlane_b32 s5, v254, 15
	s_add_u32 s4, s4, s6
	v_lshlrev_b32_e32 v22, 3, v52
	v_add_u32_e32 v18, 32, v16
	s_addc_u32 s5, s5, s7
	v_and_b32_e32 v0, 0x78, v22
	v_ashrrev_i32_e32 v17, 31, v16
	v_ashrrev_i32_e32 v19, 31, v18
	s_add_u32 s6, s3, s6
	v_lshlrev_b32_e32 v23, 1, v0
	v_lshlrev_b64 v[48:49], 8, v[16:17]
	s_waitcnt vmcnt(8)
	v_lshlrev_b64 v[12:13], 8, v[18:19]
	s_addc_u32 s7, s11, s7
	v_or_b32_e32 v50, v48, v23
	v_mov_b32_e32 v51, v49
	v_or_b32_e32 v12, v12, v23
	v_lshl_add_u64 v[0:1], s[6:7], 0, v[50:51]
	v_lshl_add_u64 v[4:5], s[6:7], 0, v[12:13]
	s_barrier
	global_load_dwordx4 v[0:3], v[0:1], off
	s_nop 0
	global_load_dwordx4 v[4:7], v[4:5], off
	v_lshl_add_u64 v[8:9], s[4:5], 0, v[50:51]
	global_load_dwordx4 v[8:11], v[8:9], off
	v_lshl_add_u64 v[12:13], s[4:5], 0, v[12:13]
	v_readfirstlane_b32 s17, v52
	global_load_dwordx4 v[12:15], v[12:13], off
	s_ashr_i32 s20, s17, 1
	v_mov_b32_e32 v17, s20
	s_movk_i32 s21, 0xffe0
	v_bfe_u32 v182, v52, 5, 1
	v_bfi_b32 v17, s21, v17, v52
	v_mov_b64_e32 v[20:21], s[8:9]
	s_movk_i32 s8, 0xc00
	v_mad_i64_i32 v[20:21], s[8:9], v17, s8, v[20:21]
	v_lshlrev_b32_e32 v176, 4, v182
	v_lshl_add_u64 v[20:21], v[20:21], 0, v[176:177]
	global_load_dwordx4 v[120:123], v[20:21], off
	global_load_dwordx4 v[112:115], v[20:21], off offset:32
	global_load_dwordx4 v[124:127], v[20:21], off offset:64
	global_load_dwordx4 v[116:119], v[20:21], off offset:96
	global_load_dwordx4 v[108:111], v[20:21], off offset:128
	global_load_dwordx4 v[104:107], v[20:21], off offset:160
	global_load_dwordx4 v[100:103], v[20:21], off offset:192
	global_load_dwordx4 v[96:99], v[20:21], off offset:224
	s_mov_b64 s[98:99], 0x4000
	v_lshl_add_u64 v[248:249], v[50:51], 0, s[98:99]
	v_lshl_add_u64 v[250:251], s[6:7], 0, v[248:249]
	global_load_dwordx4 v[200:203], v[250:251], off
	v_lshl_add_u64 v[250:251], s[4:5], 0, v[248:249]
	global_load_dwordx4 v[208:211], v[250:251], off
	s_mov_b64 s[98:99], 0x6000
	v_lshl_add_u64 v[248:249], v[50:51], 0, s[98:99]
	v_lshl_add_u64 v[250:251], s[6:7], 0, v[248:249]
	global_load_dwordx4 v[204:207], v[250:251], off
	v_lshl_add_u64 v[250:251], s[4:5], 0, v[248:249]
	global_load_dwordx4 v[212:215], v[250:251], off
	v_and_b32_e32 v17, 0xfffff0, v16
	v_lshlrev_b32_e32 v19, 1, v16
	v_lshrrev_b32_e32 v24, 1, v16
	v_and_b32_e32 v25, 3, v16
	v_and_or_b32 v17, v16, 8, v17
	v_and_or_b32 v19, v16, 4, v25
	v_and_b32_e32 v24, 0xfffff0, v18
	v_lshlrev_b32_e32 v25, 1, v18
	v_bfe_u32 v22, v22, 5, 2
	v_lshrrev_b32_e32 v17, 1, v17
	v_and_or_b32 v24, v18, 8, v24
	v_or_b32_e32 v17, v17, v22
	v_lshrrev_b32_e32 v24, 1, v24
	v_lshlrev_b32_e32 v19, 6, v19
	v_and_b32_e32 v26, 48, v23
	v_lshlrev_b32_e32 v17, 9, v17
	v_or_b32_e32 v22, v24, v22
	v_or3_b32 v17, v17, v19, v26
	v_lshlrev_b32_e32 v22, 9, v22
	v_or3_b32 v19, v22, v19, v26
	v_add_u32_e32 v188, 0, v17
	v_add_u32_e32 v189, 0, v19
	s_waitcnt vmcnt(4)
	v_and_b32_e32 v183, 31, v52
	v_lshlrev_b32_e32 v53, 4, v52
	v_and_b32_e32 v76, 63, v52
	s_mov_b64 s[36:37], 0x4000
	v_lshl_add_u64 v[62:63], v[50:51], 0, s[36:37]
	s_mov_b64 s[36:37], 0x6000
	s_waitcnt vmcnt(11)
	ds_write_b128 v188, v[0:3]
	s_waitcnt vmcnt(10)
	ds_write_b128 v189, v[4:7]
	v_lshlrev_b32_e32 v0, 8, v16
	v_and_b32_e32 v1, 0xf0, v52
	v_bitop3_b32 v0, v23, v0, v1 bitop3:0xde
	v_add_u32_e32 v190, 0, v0
	v_lshlrev_b32_e32 v0, 8, v18
	s_waitcnt vmcnt(9)
	ds_write_b128 v190, v[8:11] offset:32768
	v_bitop3_b32 v0, v23, v0, v1 bitop3:0xde
	v_lshlrev_b32_e32 v8, 8, v183
	v_and_b32_e32 v9, 0xf0, v53
	v_add_u32_e32 v191, 0, v0
	v_bitop3_b32 v0, v176, v8, v9 bitop3:0xde
	v_add_u32_e32 v192, 0, v0
	s_waitcnt vmcnt(8)
	ds_write_b128 v191, v[12:15] offset:32768
	s_waitcnt lgkmcnt(0)
	s_barrier
; __device__ __forceinline__ void partialSM(f32x16& p0, f32x16& p1, float& m_reg, float& mn, float& alpha) {
;   constexpr float C = SCALE * 1.4426950408889634f;
;   float pmax = p0[0]; for (int r = 1; r < 16; ++r) pmax = fmaxf(pmax, p0[r]); for (int r = 0; r < 16; ++r) pmax = fmaxf(pmax, p1[r]);
;   { auto rr = __builtin_amdgcn_permlane32_swap(__float_as_uint(pmax), __float_as_uint(pmax), false, false);
;     pmax = fmaxf(__uint_as_float(rr[0]), __uint_as_float(rr[1])); }
; __device__ __forceinline__ void qkt(f32x16& p0, f32x16& p1, const bf16* Ks, const bf16x8* qr, int r32, int hi) {
;   p0 = f32x16{}; p1 = f32x16{};
;   for (int d0 = 0; d0 < 8; ++d0) { int cb = (d0 * 16 + hi * 8) * 2;
;     bf16x8 b0 = *reinterpret_cast<const bf16x8*>((const char*)Ks + KSWZ(r32, cb));
;     bf16x8 b1 = *reinterpret_cast<const bf16x8*>((const char*)Ks + KSWZ(32 + r32, cb));
;     p0 = __builtin_amdgcn_mfma_f32_32x32x16_bf16(b0, qr[d0], p0, 0, 0, 0);
;     p1 = __builtin_amdgcn_mfma_f32_32x32x16_bf16(b1, qr[d0], p1, 0, 0, 0); }
; }
	ds_read_b128 v[0:3], v192 offset:32768
	ds_read_b128 v[4:7], v192 offset:40960
	s_waitcnt vmcnt(7) lgkmcnt(1)
	v_mfma_f32_32x32x16_bf16 v[32:47], v[0:3], v[120:123], 0
	v_or_b32_e32 v0, 32, v176
	v_bitop3_b32 v0, v0, v8, v9 bitop3:0xde
	v_add_u32_e32 v199, 0, v0
	v_lshlrev_b32_e32 v10, 3, v76
	v_lshlrev_b32_e32 v12, 1, v52
	v_lshl_add_u64 v[64:65], v[50:51], 0, s[36:37]
	v_lshl_add_u64 v[58:59], s[6:7], 0, v[64:65]
	s_waitcnt lgkmcnt(0)
	v_mfma_f32_32x32x16_bf16 v[16:31], v[4:7], v[120:123], 0
	ds_read_b128 v[0:3], v199 offset:32768
	ds_read_b128 v[4:7], v199 offset:40960
	v_lshl_add_u64 v[66:67], s[4:5], 0, v[64:65]
	s_mov_b64 s[36:37], 0xa000
	s_and_b32 s8, s17, 0x3fffffc0
	s_lshl_b32 s8, s8, 2
	s_add_i32 s8, s8, 0
	s_add_i32 s8, s8, 0x10000
	s_waitcnt vmcnt(6) lgkmcnt(1)
	v_mfma_f32_32x32x16_bf16 v[32:47], v[0:3], v[112:115], v[32:47]
	v_or_b32_e32 v0, 64, v176
	v_bitop3_b32 v0, v0, v8, v9 bitop3:0xde
	v_add_u32_e32 v198, 0, v0
	s_andn2_b32 s20, s20, 31
	s_cmp_lg_u32 0, -1
	s_cselect_b32 s9, 0, 0
	s_mov_b32 s57, s56
	s_waitcnt lgkmcnt(0)
	v_mfma_f32_32x32x16_bf16 v[16:31], v[4:7], v[112:115], v[16:31]
	ds_read_b128 v[0:3], v198 offset:32768
	ds_read_b128 v[4:7], v198 offset:40960
	s_mov_b32 s58, s56
	s_mov_b32 s59, s56
	s_mov_b32 s60, s56
	s_mov_b32 s61, s56
	s_mov_b32 s62, s56
	s_mov_b32 s63, s56
	s_waitcnt vmcnt(5) lgkmcnt(1)
	v_mfma_f32_32x32x16_bf16 v[32:47], v[0:3], v[124:127], v[32:47]
	v_or_b32_e32 v0, 0x60, v176
	v_bitop3_b32 v0, v0, v8, v9 bitop3:0xde
	v_add_u32_e32 v195, 0, v0
	s_mov_b32 s64, s56
	s_mov_b32 s65, s56
	s_mov_b32 s66, s56
	s_mov_b32 s67, s56
	s_waitcnt lgkmcnt(0)
	v_mfma_f32_32x32x16_bf16 v[16:31], v[4:7], v[124:127], v[16:31]
	ds_read_b128 v[0:3], v195 offset:32768
	ds_read_b128 v[4:7], v195 offset:40960
	s_mov_b32 s68, s56
	s_mov_b32 s69, s56
	s_mov_b32 s70, s56
	s_mov_b32 s71, s56
	v_lshl_add_u32 v184, v183, 2, s8
	v_mov_b32_e32 v185, 0
	s_waitcnt vmcnt(4) lgkmcnt(1)
	v_mfma_f32_32x32x16_bf16 v[32:47], v[0:3], v[116:119], v[32:47]
	v_or_b32_e32 v0, 0x80, v176
	v_bitop3_b32 v0, v0, v8, v9 bitop3:0xde
	v_add_u32_e32 v194, 0, v0
	s_waitcnt lgkmcnt(0)
	v_mfma_f32_32x32x16_bf16 v[16:31], v[4:7], v[116:119], v[16:31]
	ds_read_b128 v[0:3], v194 offset:32768
	ds_read_b128 v[4:7], v194 offset:40960
	s_waitcnt vmcnt(4) lgkmcnt(1)
	v_mfma_f32_32x32x16_bf16 v[32:47], v[0:3], v[108:111], v[32:47]
	v_or_b32_e32 v0, 0xa0, v176
	v_bitop3_b32 v0, v0, v8, v9 bitop3:0xde
	v_add_u32_e32 v193, 0, v0
	ds_read_b128 v[0:3], v193 offset:32768
	s_waitcnt lgkmcnt(1)
	v_mfma_f32_32x32x16_bf16 v[16:31], v[4:7], v[108:111], v[16:31]
	ds_read_b128 v[4:7], v193 offset:40960
	s_waitcnt vmcnt(4) lgkmcnt(1)
	v_mfma_f32_32x32x16_bf16 v[32:47], v[0:3], v[104:107], v[32:47]
	v_and_b32_e32 v0, 0xc0, v53
	v_and_or_b32 v11, v10, 24, v0
	v_or_b32_e32 v0, 0xc0, v176
	v_bitop3_b32 v0, v0, v8, v9 bitop3:0xde
	v_add_u32_e32 v196, 0, v0
	ds_read_b128 v[0:3], v196 offset:32768
	s_waitcnt lgkmcnt(1)
	v_mfma_f32_32x32x16_bf16 v[16:31], v[4:7], v[104:107], v[16:31]
	v_and_b32_e32 v4, 32, v12
	v_and_b32_e32 v5, 0x100, v10
	v_or3_b32 v53, v11, v4, v5
	ds_read_b128 v[4:7], v196 offset:40960
	v_add_u32_e32 v187, s9, v53
	s_waitcnt vmcnt(4) lgkmcnt(1)
	v_mfma_f32_32x32x16_bf16 v[32:47], v[0:3], v[100:103], v[32:47]
	v_or_b32_e32 v0, 0xe0, v176
	v_bitop3_b32 v0, v0, v8, v9 bitop3:0xde
	v_add_u32_e32 v197, 0, v0
	ds_read_b128 v[0:3], v197 offset:32768
	ds_read_b128 v[54:57], v197 offset:40960
	s_waitcnt lgkmcnt(2)
	v_mfma_f32_32x32x16_bf16 v[16:31], v[4:7], v[100:103], v[16:31]
	s_waitcnt vmcnt(4) lgkmcnt(1)
	v_mfma_f32_32x32x16_bf16 v[32:47], v[0:3], v[96:99], v[32:47]
	v_mov_b64_e32 v[0:1], s[56:57]
	v_mov_b64_e32 v[14:15], s[70:71]
	v_mov_b64_e32 v[2:3], s[58:59]
	v_mov_b64_e32 v[4:5], s[60:61]
	v_mov_b64_e32 v[6:7], s[62:63]
	v_mov_b64_e32 v[8:9], s[64:65]
	v_mov_b64_e32 v[10:11], s[66:67]
	s_waitcnt lgkmcnt(0)
	v_mfma_f32_32x32x16_bf16 v[16:31], v[54:57], v[96:99], v[16:31]
	s_nop 2
	v_max_f32_e32 v54, v33, v33
	v_max_f32_e32 v55, v32, v32
	v_max_f32_e32 v54, v55, v54
	v_max3_f32 v54, v54, v34, v35
	v_max3_f32 v54, v54, v36, v37
	v_max3_f32 v54, v54, v38, v39
	v_max3_f32 v54, v54, v40, v41
	v_max3_f32 v54, v54, v42, v43
	v_max3_f32 v54, v54, v44, v45
	v_max3_f32 v54, v54, v46, v47
	v_max3_f32 v70, v54, v16, v17
	v_max3_f32 v70, v70, v18, v19
	v_max3_f32 v70, v70, v20, v21
	v_max3_f32 v70, v70, v22, v23
	v_max3_f32 v70, v70, v24, v25
	v_max3_f32 v70, v70, v26, v27
	v_lshl_add_u64 v[54:55], s[6:7], 0, v[62:63]
	v_lshl_add_u64 v[62:63], s[4:5], 0, v[62:63]
	v_max3_f32 v70, v70, v28, v29
	s_waitcnt vmcnt(0)
; #define SLOAD(i, k0) do { sr_[i].vs0 = St::ld8(&Vh[(long)((k0) + sr) * LDK + sc]); sr_[i].vs1 = St::ld8(&Vh[(long)((k0) + 32 + sr) * LDK + sc]); \
;     sr_[i].ks0 = St::ld8(&Kh[(long)((k0) + sr) * LDK + sc]); sr_[i].ks1 = St::ld8(&Kh[(long)((k0) + 32 + sr) * LDK + sc]); } while (0)
; #define SWAIT() do { if constexpr (SDEPTH == 2) asm volatile("s_waitcnt vmcnt(4)" ::: "memory"); else asm volatile("s_waitcnt vmcnt(0)" ::: "memory"); } while (0)
; __device__ __forceinline__ void partialSM(f32x16& p0, f32x16& p1, float& m_reg, float& mn, float& alpha) {
;   constexpr float C = SCALE * 1.4426950408889634f;
;   float pmax = p0[0]; for (int r = 1; r < 16; ++r) pmax = fmaxf(pmax, p0[r]); for (int r = 0; r < 16; ++r) pmax = fmaxf(pmax, p1[r]);
;   { auto rr = __builtin_amdgcn_permlane32_swap(__float_as_uint(pmax), __float_as_uint(pmax), false, false);
;     pmax = fmaxf(__uint_as_float(rr[0]), __uint_as_float(rr[1])); }
;   if (__builtin_expect(__all(pmax - m_reg <= THR / SCALE), 1)) { mn = m_reg; alpha = 1.f; }
;   else { mn = fmaxf(m_reg, pmax); alpha = __builtin_amdgcn_exp2f((m_reg - mn) * C); m_reg = mn; }
;   float mnC = -mn * C;
;   for (int r = 0; r < 16; ++r) p0[r] = fmaf(p0[r], C, mnC); for (int r = 0; r < 16; ++r) p1[r] = fmaf(p1[r], C, mnC);
;   for (int r = 0; r < 16; ++r) p0[r] = __builtin_amdgcn_exp2f(p0[r]);
; }
; template <typename TQ>
; __device__ __forceinline__ void attn_dense_body(const TQ* __restrict__ Qb, const bf16* __restrict__ Kh, const bf16* __restrict__ Vh,
;                                                 bf16* __restrict__ Ob, int seq, char* lds, const int tid) {
;     ...
;   qkt(pA0, pA1, K_lds, qr, r32, hi); partialSM(pA0, pA1, m_reg, mnA, alA);
;   SLOAD(SO, KVBLK); if constexpr (SDEPTH == 2) { if (2 < NT) SLOAD(SE, 2 * KVBLK); }
;   SWAIT(); SWRITE(1, SO); __syncthreads();
	v_mov_b32_e32 v54, v200
	v_mov_b32_e32 v55, v201
	v_mov_b32_e32 v56, v202
	v_mov_b32_e32 v57, v203
	s_nop 0
	v_mov_b32_e32 v58, v204
	v_mov_b32_e32 v59, v205
	v_mov_b32_e32 v60, v206
	v_mov_b32_e32 v61, v207
	s_nop 0
	v_mov_b32_e32 v62, v208
	v_mov_b32_e32 v63, v209
	v_mov_b32_e32 v64, v210
	v_mov_b32_e32 v65, v211
	s_nop 0
	v_mov_b32_e32 v66, v212
	v_mov_b32_e32 v67, v213
	v_mov_b32_e32 v68, v214
	v_mov_b32_e32 v69, v215
	s_nop 0
	s_nop 0
	s_nop 0
	s_nop 0
	s_nop 0
	s_nop 0
	s_nop 0
	s_nop 0
	s_nop 0
	s_nop 0
	s_nop 0
	s_nop 0
	s_nop 0
	s_nop 0
	s_nop 0
	v_max3_f32 v77, v70, v30, v31
	v_lshl_add_u64 v[70:71], v[50:51], 0, s[12:13]
	v_lshl_add_u64 v[72:73], s[6:7], 0, v[70:71]
	v_lshl_add_u64 v[50:51], v[50:51], 0, s[36:37]
	v_lshl_add_u64 v[70:71], s[4:5], 0, v[70:71]
	v_lshl_add_u64 v[74:75], s[6:7], 0, v[50:51]
	global_load_dwordx4 v[128:131], v[72:73], off
	global_load_dwordx4 v[136:139], v[74:75], off
	v_lshl_add_u64 v[50:51], s[4:5], 0, v[50:51]
	global_load_dwordx4 v[132:135], v[70:71], off
	global_load_dwordx4 v[140:143], v[50:51], off
	v_mov_b32_e32 v78, v77
	s_nop 1
	v_permlane32_swap_b32_e32 v77, v78
	v_max_f32_e32 v50, v78, v78
	v_max_f32_e32 v51, v77, v77
	v_max_f32_e32 v50, v51, v50
	v_add_f32_e32 v51, 0x7149f2ca, v50
	v_max_f32_e32 v50, 0xf149f2ca, v50
	v_cmp_ge_f32_e32 vcc, s14, v51
	v_sub_f32_e32 v51, 0xf149f2ca, v50
	v_mul_f32_e32 v51, 0x3e0293ee, v51
	v_exp_f32_e32 v51, v51
	s_cmp_eq_u64 vcc, exec
	s_cselect_b64 vcc, -1, 0
	v_cndmask_b32_e32 v164, v50, v180, vcc
	v_mul_f32_e32 v50, 0xbe0293ee, v164
	v_cndmask_b32_e64 v200, v51, 1.0, vcc
	v_mov_b32_e32 v51, v50
	v_fmamk_f32 v32, v32, 0x3e0293ee, v50
	v_fmamk_f32 v33, v33, 0x3e0293ee, v50
	v_fmamk_f32 v34, v34, 0x3e0293ee, v50
	v_fmamk_f32 v35, v35, 0x3e0293ee, v50
	v_fmamk_f32 v36, v36, 0x3e0293ee, v50
	v_fmamk_f32 v37, v37, 0x3e0293ee, v50
	v_fmamk_f32 v38, v38, 0x3e0293ee, v50
	v_fmamk_f32 v39, v39, 0x3e0293ee, v50
	v_fmamk_f32 v40, v40, 0x3e0293ee, v50
	v_fmamk_f32 v41, v41, 0x3e0293ee, v50
	v_fmamk_f32 v42, v42, 0x3e0293ee, v50
	v_fmamk_f32 v43, v43, 0x3e0293ee, v50
	v_fmamk_f32 v44, v44, 0x3e0293ee, v50
	v_fmamk_f32 v45, v45, 0x3e0293ee, v50
	v_fmamk_f32 v46, v46, 0x3e0293ee, v50
	v_fmac_f32_e32 v51, 0x3e0293ee, v47
	v_pk_fma_f32 v[154:155], v[18:19], s[10:11], v[50:51] op_sel_hi:[1,0,0]
	v_pk_fma_f32 v[156:157], v[16:17], s[10:11], v[50:51] op_sel_hi:[1,0,0]
	v_exp_f32_e32 v161, v32
	v_exp_f32_e32 v162, v33
	v_exp_f32_e32 v174, v34
	v_exp_f32_e32 v175, v35
	v_exp_f32_e32 v204, v36
	v_exp_f32_e32 v207, v37
	v_exp_f32_e32 v163, v38
	v_exp_f32_e32 v173, v39
	v_exp_f32_e32 v168, v40
	v_exp_f32_e32 v170, v41
	v_exp_f32_e32 v171, v42
	v_exp_f32_e32 v172, v43
	v_exp_f32_e32 v165, v44
	v_exp_f32_e32 v166, v45
	v_exp_f32_e32 v167, v46
	v_exp_f32_e32 v169, v51
	v_mad_i64_i32 v[16:17], s[4:5], s16, v181, v[48:49]
	v_and_b32_e32 v18, 15, v52
	s_waitcnt vmcnt(4)
	s_addk_i32 s9, 0x4000
	v_lshl_or_b32 v16, v18, 4, v16
	v_mov_b64_e32 v[12:13], s[68:69]
	v_pk_fma_f32 v[150:151], v[30:31], s[10:11], v[50:51] op_sel_hi:[1,0,0]
	v_pk_fma_f32 v[152:153], v[28:29], s[10:11], v[50:51] op_sel_hi:[1,0,0]
	v_pk_fma_f32 v[158:159], v[26:27], s[10:11], v[50:51] op_sel_hi:[1,0,0]
	v_pk_fma_f32 v[144:145], v[24:25], s[10:11], v[50:51] op_sel_hi:[1,0,0]
	v_pk_fma_f32 v[146:147], v[22:23], s[10:11], v[50:51] op_sel_hi:[1,0,0]
	v_pk_fma_f32 v[148:149], v[20:21], s[10:11], v[50:51] op_sel_hi:[1,0,0]
	s_waitcnt vmcnt(7)
	ds_write_b128 v188, v[54:57] offset:16384
	s_waitcnt vmcnt(6)
	ds_write_b128 v189, v[58:61] offset:16384
	s_waitcnt vmcnt(5)
	ds_write_b128 v190, v[62:65] offset:49152
	s_waitcnt vmcnt(4)
	ds_write_b128 v191, v[66:69] offset:49152
	v_add_u32_e32 v186, s9, v53
	v_lshl_add_u64 v[178:179], s[0:1], 0, v[16:17]
	v_mov_b64_e32 v[62:63], v[14:15]
	v_mov_b64_e32 v[46:47], v[14:15]
	v_mov_b64_e32 v[30:31], v[14:15]
	v_cmp_gt_u32_e64 s[36:37], 32, v76
	v_mov_b64_e32 v[60:61], v[12:13]
	v_mov_b64_e32 v[58:59], v[10:11]
	v_mov_b64_e32 v[56:57], v[8:9]
	v_mov_b64_e32 v[54:55], v[6:7]
	v_mov_b64_e32 v[52:53], v[4:5]
	v_mov_b64_e32 v[50:51], v[2:3]
	v_mov_b64_e32 v[48:49], v[0:1]
	v_mov_b64_e32 v[44:45], v[12:13]
	v_mov_b64_e32 v[42:43], v[10:11]
	v_mov_b64_e32 v[40:41], v[8:9]
	v_mov_b64_e32 v[38:39], v[6:7]
	v_mov_b64_e32 v[36:37], v[4:5]
	v_mov_b64_e32 v[34:35], v[2:3]
	v_mov_b64_e32 v[32:33], v[0:1]
	v_mov_b64_e32 v[28:29], v[12:13]
	v_mov_b64_e32 v[26:27], v[10:11]
	v_mov_b64_e32 v[24:25], v[8:9]
	v_mov_b64_e32 v[22:23], v[6:7]
	v_mov_b64_e32 v[20:21], v[4:5]
	v_mov_b64_e32 v[18:19], v[2:3]
	v_mov_b64_e32 v[16:17], v[0:1]
	s_mov_b32 s9, 1
	s_waitcnt lgkmcnt(0)
	s_barrier
